# PV pipelining extended through the last value block (rounds 5..31)
# speedup vs baseline: 1.0072x; 1.0072x over previous
; #define LAS __attribute__((address_space(3)))
; __device__ __forceinline__ unsigned pk2(float lo, float hi) { f32x2_t v = {lo, hi}; bf16x2_t b = __builtin_convertvector(v, bf16x2_t); return __builtin_bit_cast(unsigned, b); }
; __device__ __forceinline__ void attn_unit(const Args& c, int l, int b, int h, int qb, float lam, float lam_init, LAS unsigned char* lds) {
;     ...
;             const float mnew = fmaxf(mrow[m], mx);
;             const float alpha = __builtin_amdgcn_exp2f(mrow[m] - mnew);
;             mrow[m] = mnew;
;             float ps = 0.f;
; #pragma unroll
;             for (int kb = 0; kb < 8; ++kb)
; #pragma unroll
;                 for (int e = 0; e < 4; ++e) { s[kb][e] = __builtin_amdgcn_exp2f(s[kb][e] - mnew); ps += s[kb][e]; }
;             lrow[m] = lrow[m] * alpha + ps;
;             if (__builtin_amdgcn_ballot_w64(alpha != 1.0f) != 0ull) {
; #pragma unroll
;                 for (int vb = 0; vb < 8; ++vb) O[m][vb] = O[m][vb] * alpha;
;             }
; #pragma unroll
;             for (int s2 = 0; s2 < 4; ++s2) { u32x4v o; o.x = pk2(s[2 * s2][0], s[2 * s2][1]); o.y = pk2(s[2 * s2][2], s[2 * s2][3]); o.z = pk2(s[2 * s2 + 1][0], s[2 * s2 + 1][1]); o.w = pk2(s[2 * s2 + 1][2], s[2 * s2 + 1][3]);
;                 pf[m][s2] = __builtin_bit_cast(bf16x8, o); }
;         }
; #pragma unroll
;         for (int vb = 0; vb < 8; ++vb)
; #pragma unroll
;             for (int s2 = 0; s2 < 4; ++s2) {
;                 const v4i16_t lo = __builtin_amdgcn_ds_read_tr16_b64_v4i16((LAS v4i16_t*)(Vs + (32 * s2 + 4 * q4 + r4) * 136 + 16 * vb + 4 * c4));
;                 const v4i16_t hi = __builtin_amdgcn_ds_read_tr16_b64_v4i16((LAS v4i16_t*)(Vs + (32 * s2 + 16 + 4 * q4 + r4) * 136 + 16 * vb + 4 * c4));
;                 const bf16x8 vfr = (bf16x8){lo[0], lo[1], lo[2], lo[3], hi[0], hi[1], hi[2], hi[3]};
.LBB0_255:
	v_sub_f32_e32 v174, v174, v214
	v_exp_f32_e32 v174, v174
	v_sub_f32_e32 v175, v175, v214
	v_exp_f32_e32 v175, v175
	v_sub_f32_e32 v176, v176, v214
	v_exp_f32_e32 v176, v176
	v_sub_f32_e32 v177, v177, v214
	v_exp_f32_e32 v177, v177
	v_sub_f32_e32 v170, v170, v214
	v_add_f32_e32 v180, 0, v174
	v_exp_f32_e32 v170, v170
	v_sub_f32_e32 v171, v171, v214
	v_add_f32_e32 v180, v175, v180
	v_exp_f32_e32 v171, v171
	v_sub_f32_e32 v172, v172, v214
	v_add_f32_e32 v180, v176, v180
	v_exp_f32_e32 v172, v172
	v_sub_f32_e32 v173, v173, v214
	v_add_f32_e32 v180, v177, v180
	v_exp_f32_e32 v173, v173
	v_sub_f32_e32 v166, v166, v214
	v_add_f32_e32 v180, v170, v180
	v_exp_f32_e32 v166, v166
	v_sub_f32_e32 v167, v167, v214
	v_add_f32_e32 v180, v171, v180
	v_exp_f32_e32 v167, v167
	v_sub_f32_e32 v168, v168, v214
	v_add_f32_e32 v180, v172, v180
	v_exp_f32_e32 v168, v168
	v_sub_f32_e32 v169, v169, v214
	v_add_f32_e32 v180, v173, v180
	v_exp_f32_e32 v169, v169
	v_sub_f32_e32 v162, v162, v214
	v_add_f32_e32 v180, v166, v180
	v_exp_f32_e32 v162, v162
	v_sub_f32_e32 v163, v163, v214
	v_add_f32_e32 v180, v167, v180
	v_exp_f32_e32 v163, v163
	v_sub_f32_e32 v164, v164, v214
	v_add_f32_e32 v180, v168, v180
	v_exp_f32_e32 v164, v164
	v_sub_f32_e32 v165, v165, v214
	v_add_f32_e32 v180, v169, v180
	v_exp_f32_e32 v165, v165
	v_sub_f32_e32 v158, v158, v214
	v_add_f32_e32 v180, v162, v180
	v_exp_f32_e32 v158, v158
	v_sub_f32_e32 v159, v159, v214
	v_add_f32_e32 v180, v163, v180
	v_exp_f32_e32 v159, v159
	v_sub_f32_e32 v160, v160, v214
	v_add_f32_e32 v180, v164, v180
	v_exp_f32_e32 v160, v160
	v_sub_f32_e32 v161, v161, v214
	v_add_f32_e32 v180, v165, v180
	v_exp_f32_e32 v161, v161
	v_sub_f32_e32 v154, v154, v214
	v_add_f32_e32 v180, v158, v180
	v_exp_f32_e32 v154, v154
	v_sub_f32_e32 v155, v155, v214
	v_add_f32_e32 v180, v159, v180
	v_exp_f32_e32 v155, v155
	v_sub_f32_e32 v156, v156, v214
	v_add_f32_e32 v180, v160, v180
	v_exp_f32_e32 v156, v156
	v_sub_f32_e32 v157, v157, v214
	v_add_f32_e32 v180, v161, v180
	v_exp_f32_e32 v157, v157
	v_sub_f32_e32 v150, v150, v214
	v_add_f32_e32 v180, v154, v180
	v_exp_f32_e32 v150, v150
	v_sub_f32_e32 v151, v151, v214
	v_add_f32_e32 v180, v155, v180
	v_exp_f32_e32 v151, v151
	v_sub_f32_e32 v152, v152, v214
	v_add_f32_e32 v180, v156, v180
	v_exp_f32_e32 v152, v152
	v_sub_f32_e32 v153, v153, v214
	v_add_f32_e32 v180, v157, v180
	v_exp_f32_e32 v153, v153
	v_sub_f32_e32 v146, v146, v214
	v_add_f32_e32 v180, v150, v180
	v_exp_f32_e32 v181, v146
	v_add_f32_e32 v180, v151, v180
	v_add_f32_e32 v180, v152, v180
	v_add_f32_e32 v180, v153, v180
	v_sub_f32_e32 v147, v147, v214
	v_add_f32_e32 v146, v181, v180
	v_exp_f32_e32 v180, v147
	v_sub_f32_e32 v147, v148, v214
	v_exp_f32_e32 v148, v147
	v_sub_f32_e32 v147, v149, v214
	v_exp_f32_e32 v149, v147
	v_sub_f32_e32 v114, v114, v213
	v_add_f32_e32 v146, v180, v146
	v_exp_f32_e32 v147, v114
	v_sub_f32_e32 v114, v115, v213
	v_add_f32_e32 v146, v148, v146
	v_exp_f32_e32 v182, v114
	v_sub_f32_e32 v114, v116, v213
	v_add_f32_e32 v146, v149, v146
	v_exp_f32_e32 v183, v114
	v_sub_f32_e32 v114, v117, v213
	v_fmac_f32_e32 v146, v216, v192
	v_exp_f32_e32 v192, v114
	v_sub_f32_e32 v114, v118, v213
	v_exp_f32_e32 v118, v114
	v_sub_f32_e32 v114, v119, v213
	v_exp_f32_e32 v119, v114
	v_sub_f32_e32 v114, v120, v213
	v_exp_f32_e32 v120, v114
	v_sub_f32_e32 v114, v121, v213
	v_exp_f32_e32 v121, v114
	v_sub_f32_e32 v114, v122, v213
	v_exp_f32_e32 v216, v114
	v_sub_f32_e32 v114, v123, v213
	v_exp_f32_e32 v217, v114
	v_sub_f32_e32 v114, v124, v213
	v_exp_f32_e32 v218, v114
	v_sub_f32_e32 v114, v125, v213
	v_exp_f32_e32 v219, v114
	v_sub_f32_e32 v114, v126, v213
	v_exp_f32_e32 v220, v114
	v_sub_f32_e32 v114, v127, v213
	v_exp_f32_e32 v221, v114
	v_sub_f32_e32 v114, v128, v213
	v_exp_f32_e32 v222, v114
	v_sub_f32_e32 v114, v129, v213
	v_exp_f32_e32 v223, v114
	v_sub_f32_e32 v114, v130, v213
	v_cvt_pk_bf16_f32 v130, v147, v182
	v_add_f32_e32 v147, 0, v147
	v_add_f32_e32 v147, v182, v147
	v_add_f32_e32 v147, v183, v147
	v_exp_f32_e32 v224, v114
	v_sub_f32_e32 v114, v131, v213
	v_add_f32_e32 v147, v192, v147
	v_exp_f32_e32 v225, v114
	v_sub_f32_e32 v114, v132, v213
	v_cvt_pk_bf16_f32 v132, v118, v119
	v_add_f32_e32 v118, v118, v147
	v_add_f32_e32 v118, v119, v118
	v_add_f32_e32 v118, v120, v118
	v_add_f32_e32 v118, v121, v118
	v_add_f32_e32 v118, v216, v118
	v_add_f32_e32 v118, v217, v118
	v_add_f32_e32 v118, v218, v118
	v_add_f32_e32 v118, v219, v118
	v_add_f32_e32 v118, v220, v118
	v_add_f32_e32 v118, v221, v118
	v_exp_f32_e32 v226, v114
	v_sub_f32_e32 v114, v133, v213
	v_add_f32_e32 v118, v222, v118
	v_exp_f32_e32 v227, v114
	v_sub_f32_e32 v114, v134, v213
	v_add_f32_e32 v118, v223, v118
	v_exp_f32_e32 v134, v114
	v_sub_f32_e32 v114, v135, v213
	v_add_f32_e32 v118, v224, v118
	v_exp_f32_e32 v135, v114
	v_sub_f32_e32 v114, v136, v213
	v_add_f32_e32 v118, v225, v118
	v_exp_f32_e32 v136, v114
	v_sub_f32_e32 v114, v137, v213
	v_add_f32_e32 v118, v226, v118
	v_exp_f32_e32 v137, v114
	v_sub_f32_e32 v114, v138, v213
	v_add_f32_e32 v118, v227, v118
	v_exp_f32_e32 v138, v114
	v_sub_f32_e32 v114, v139, v213
	v_add_f32_e32 v118, v134, v118
	v_exp_f32_e32 v139, v114
	v_sub_f32_e32 v114, v140, v213
	v_add_f32_e32 v118, v135, v118
	v_exp_f32_e32 v140, v114
	v_sub_f32_e32 v114, v141, v213
	v_add_f32_e32 v118, v136, v118
	v_exp_f32_e32 v141, v114
	v_sub_f32_e32 v114, v142, v213
	v_add_f32_e32 v118, v137, v118
	v_exp_f32_e32 v142, v114
	v_sub_f32_e32 v114, v143, v213
	v_add_f32_e32 v118, v138, v118
	v_exp_f32_e32 v143, v114
	v_sub_f32_e32 v114, v144, v213
	v_add_f32_e32 v118, v139, v118
	v_exp_f32_e32 v144, v114
	v_sub_f32_e32 v114, v145, v213
	v_add_f32_e32 v118, v140, v118
	v_exp_f32_e32 v145, v114
	v_add_f32_e32 v118, v141, v118
	v_add_f32_e32 v118, v142, v118
	v_add_f32_e32 v118, v143, v118
	v_add_f32_e32 v118, v144, v118
	v_cvt_pk_bf16_f32 v133, v120, v121
	v_add_f32_e32 v147, v145, v118
	v_cvt_pk_bf16_f32 v118, v150, v151
	v_cvt_pk_bf16_f32 v119, v152, v153
	v_cvt_pk_bf16_f32 v121, v148, v149
	ds_read_b64_tr_b16 v[150:151], v210 offset:39168
	ds_read_b64_tr_b16 v[148:149], v210 offset:34816
	ds_read_b64_tr_b16 v[152:153], v210 offset:34848
	v_cvt_pk_bf16_f32 v131, v183, v192
	v_cvt_pk_bf16_f32 v116, v142, v143
	v_cvt_pk_bf16_f32 v117, v144, v145
	v_cvt_pk_bf16_f32 v142, v174, v175
	v_cvt_pk_bf16_f32 v143, v176, v177
	v_cvt_pk_bf16_f32 v144, v170, v171
	v_cvt_pk_bf16_f32 v145, v172, v173
	s_waitcnt lgkmcnt(0)
; #define LAS __attribute__((address_space(3)))
; #define MFMA16(a, b, c) __builtin_amdgcn_mfma_f32_16x16x32_bf16(a, b, c, 0, 0, 0)
; __device__ __forceinline__ void attn_unit(const Args& c, int l, int b, int h, int qb, float lam, float lam_init, LAS unsigned char* lds) {
;     ...
; #pragma unroll
;         for (int vb = 0; vb < 8; ++vb)
; #pragma unroll
;             for (int s2 = 0; s2 < 4; ++s2) {
;                 const v4i16_t lo = __builtin_amdgcn_ds_read_tr16_b64_v4i16((LAS v4i16_t*)(Vs + (32 * s2 + 4 * q4 + r4) * 136 + 16 * vb + 4 * c4));
;                 const v4i16_t hi = __builtin_amdgcn_ds_read_tr16_b64_v4i16((LAS v4i16_t*)(Vs + (32 * s2 + 16 + 4 * q4 + r4) * 136 + 16 * vb + 4 * c4));
;                 const bf16x8 vfr = (bf16x8){lo[0], lo[1], lo[2], lo[3], hi[0], hi[1], hi[2], hi[3]};
;                 O[0][vb] = MFMA16(vfr, pf[0][s2], O[0][vb]); O[1][vb] = MFMA16(vfr, pf[1][s2], O[1][vb]);
;             }
	v_mfma_f32_16x16x32_bf16 v[46:49], v[148:151], v[130:133], v[46:49]
	v_cvt_pk_bf16_f32 v126, v216, v217
	v_cvt_pk_bf16_f32 v127, v218, v219
	v_cvt_pk_bf16_f32 v128, v220, v221
	v_mfma_f32_16x16x32_bf16 v[42:45], v[148:151], v[142:145], v[42:45]
	ds_read_b64_tr_b16 v[148:149], v210 offset:43520
	ds_read_b64_tr_b16 v[150:151], v210 offset:47872
	v_cvt_pk_bf16_f32 v129, v222, v223
	v_cvt_pk_bf16_f32 v114, v138, v139
	v_cvt_pk_bf16_f32 v115, v140, v141
	v_cvt_pk_bf16_f32 v138, v166, v167
	v_cvt_pk_bf16_f32 v139, v168, v169
	v_cvt_pk_bf16_f32 v140, v162, v163
	v_cvt_pk_bf16_f32 v141, v164, v165
	s_waitcnt lgkmcnt(0)
	v_mfma_f32_16x16x32_bf16 v[46:49], v[148:151], v[126:129], v[46:49]
	v_cvt_pk_bf16_f32 v122, v224, v225
	v_cvt_pk_bf16_f32 v123, v226, v227
	v_cvt_pk_bf16_f32 v124, v134, v135
	v_mfma_f32_16x16x32_bf16 v[42:45], v[148:151], v[138:141], v[42:45]
	ds_read_b64_tr_b16 v[148:149], v210 offset:52224
	ds_read_b64_tr_b16 v[150:151], v210 offset:56576
	v_cvt_pk_bf16_f32 v125, v136, v137
	v_cvt_pk_bf16_f32 v134, v158, v159
	v_cvt_pk_bf16_f32 v135, v160, v161
	v_cvt_pk_bf16_f32 v136, v154, v155
	v_cvt_pk_bf16_f32 v137, v156, v157
	s_waitcnt lgkmcnt(0)
	v_mfma_f32_16x16x32_bf16 v[46:49], v[148:151], v[122:125], v[46:49]
	v_cvt_pk_bf16_f32 v120, v181, v180
	s_add_i32 s35, s35, 1
	s_addk_i32 s5, 0x80
	v_mfma_f32_16x16x32_bf16 v[42:45], v[148:151], v[134:137], v[42:45]
	ds_read_b64_tr_b16 v[148:149], v210 offset:60928
	ds_read_b64_tr_b16 v[150:151], v210 offset:65280
	ds_read_b64_tr_b16 v[154:155], v210 offset:39200
	v_fmac_f32_e32 v147, v215, v190
	s_waitcnt lgkmcnt(0)
	v_mfma_f32_16x16x32_bf16 v[46:49], v[148:151], v[114:117], v[46:49]
	s_cmp_lg_u32 s34, s35
	v_mfma_f32_16x16x32_bf16 v[42:45], v[148:151], v[118:121], v[42:45]
	ds_read_b64_tr_b16 v[148:149], v210 offset:43552
	ds_read_b64_tr_b16 v[150:151], v210 offset:47904
	v_mfma_f32_16x16x32_bf16 v[38:41], v[152:155], v[130:133], v[38:41]
	v_mfma_f32_16x16x32_bf16 v[34:37], v[152:155], v[142:145], v[34:37]
	ds_read_b64_tr_b16 v[152:153], v210 offset:52256
	ds_read_b64_tr_b16 v[154:155], v210 offset:56608
	ds_read_b64_tr_b16 v[156:157], v210 offset:60960
	ds_read_b64_tr_b16 v[158:159], v210 offset:65312
	ds_read_b64_tr_b16 v[160:161], v210 offset:34880
	ds_read_b64_tr_b16 v[162:163], v210 offset:39232
	ds_read_b64_tr_b16 v[164:165], v210 offset:43584
	ds_read_b64_tr_b16 v[166:167], v210 offset:47936
	s_waitcnt lgkmcnt(8)
	v_mfma_f32_16x16x32_bf16 v[38:41], v[148:151], v[126:129], v[38:41]
	v_mfma_f32_16x16x32_bf16 v[34:37], v[148:151], v[138:141], v[34:37]
	ds_read_b64_tr_b16 v[148:149], v210 offset:52288
	ds_read_b64_tr_b16 v[150:151], v210 offset:56640
	s_waitcnt lgkmcnt(8)
	v_mfma_f32_16x16x32_bf16 v[38:41], v[152:155], v[122:125], v[38:41]
	v_mfma_f32_16x16x32_bf16 v[34:37], v[152:155], v[134:137], v[34:37]
	ds_read_b64_tr_b16 v[152:153], v210 offset:60992
	ds_read_b64_tr_b16 v[154:155], v210 offset:65344
	s_waitcnt lgkmcnt(8)
	v_mfma_f32_16x16x32_bf16 v[38:41], v[156:159], v[114:117], v[38:41]
	v_mfma_f32_16x16x32_bf16 v[34:37], v[156:159], v[118:121], v[34:37]
	ds_read_b64_tr_b16 v[156:157], v210 offset:34912
	ds_read_b64_tr_b16 v[158:159], v210 offset:39264
	s_waitcnt lgkmcnt(8)
	v_mfma_f32_16x16x32_bf16 v[30:33], v[160:163], v[130:133], v[30:33]
	v_mfma_f32_16x16x32_bf16 v[26:29], v[160:163], v[142:145], v[26:29]
	ds_read_b64_tr_b16 v[160:161], v210 offset:43616
	ds_read_b64_tr_b16 v[162:163], v210 offset:47968
	s_waitcnt lgkmcnt(8)
	v_mfma_f32_16x16x32_bf16 v[30:33], v[164:167], v[126:129], v[30:33]
	v_mfma_f32_16x16x32_bf16 v[26:29], v[164:167], v[138:141], v[26:29]
	ds_read_b64_tr_b16 v[164:165], v210 offset:52320
	ds_read_b64_tr_b16 v[166:167], v210 offset:56672
	s_waitcnt lgkmcnt(8)
	v_mfma_f32_16x16x32_bf16 v[30:33], v[148:151], v[122:125], v[30:33]
	v_mfma_f32_16x16x32_bf16 v[26:29], v[148:151], v[134:137], v[26:29]
	ds_read_b64_tr_b16 v[148:149], v210 offset:61024
	ds_read_b64_tr_b16 v[150:151], v210 offset:65376
	s_waitcnt lgkmcnt(8)
	v_mfma_f32_16x16x32_bf16 v[30:33], v[152:155], v[114:117], v[30:33]
	v_mfma_f32_16x16x32_bf16 v[26:29], v[152:155], v[118:121], v[26:29]
	ds_read_b64_tr_b16 v[152:153], v210 offset:34944
	ds_read_b64_tr_b16 v[154:155], v210 offset:39296
	s_waitcnt lgkmcnt(8)
	v_mfma_f32_16x16x32_bf16 v[62:65], v[156:159], v[130:133], v[62:65]
	v_mfma_f32_16x16x32_bf16 v[58:61], v[156:159], v[142:145], v[58:61]
	ds_read_b64_tr_b16 v[156:157], v210 offset:43648
	ds_read_b64_tr_b16 v[158:159], v210 offset:48000
	s_waitcnt lgkmcnt(8)
; #define LAS __attribute__((address_space(3)))
; #define MFMA16(a, b, c) __builtin_amdgcn_mfma_f32_16x16x32_bf16(a, b, c, 0, 0, 0)
; __device__ __forceinline__ void attn_unit(const Args& c, int l, int b, int h, int qb, float lam, float lam_init, LAS unsigned char* lds) {
;     ...
; #pragma unroll
;         for (int vb = 0; vb < 8; ++vb)
; #pragma unroll
;             for (int s2 = 0; s2 < 4; ++s2) {
;                 const v4i16_t lo = __builtin_amdgcn_ds_read_tr16_b64_v4i16((LAS v4i16_t*)(Vs + (32 * s2 + 4 * q4 + r4) * 136 + 16 * vb + 4 * c4));
;                 const v4i16_t hi = __builtin_amdgcn_ds_read_tr16_b64_v4i16((LAS v4i16_t*)(Vs + (32 * s2 + 16 + 4 * q4 + r4) * 136 + 16 * vb + 4 * c4));
;                 const bf16x8 vfr = (bf16x8){lo[0], lo[1], lo[2], lo[3], hi[0], hi[1], hi[2], hi[3]};
;                 O[0][vb] = MFMA16(vfr, pf[0][s2], O[0][vb]); O[1][vb] = MFMA16(vfr, pf[1][s2], O[1][vb]);
;             }
	v_mfma_f32_16x16x32_bf16 v[62:65], v[160:163], v[126:129], v[62:65]
	v_mfma_f32_16x16x32_bf16 v[58:61], v[160:163], v[138:141], v[58:61]
	ds_read_b64_tr_b16 v[160:161], v210 offset:52352
	ds_read_b64_tr_b16 v[162:163], v210 offset:56704
	s_waitcnt lgkmcnt(8)
	v_mfma_f32_16x16x32_bf16 v[62:65], v[164:167], v[122:125], v[62:65]
	v_mfma_f32_16x16x32_bf16 v[58:61], v[164:167], v[134:137], v[58:61]
	ds_read_b64_tr_b16 v[164:165], v210 offset:61056
	ds_read_b64_tr_b16 v[166:167], v210 offset:65408
	s_waitcnt lgkmcnt(8)
	v_mfma_f32_16x16x32_bf16 v[62:65], v[148:151], v[114:117], v[62:65]
	v_mfma_f32_16x16x32_bf16 v[58:61], v[148:151], v[118:121], v[58:61]
	ds_read_b64_tr_b16 v[148:149], v210 offset:34976
	ds_read_b64_tr_b16 v[150:151], v210 offset:39328
	s_waitcnt lgkmcnt(8)
	v_mfma_f32_16x16x32_bf16 v[22:25], v[152:155], v[130:133], v[22:25]
	v_mfma_f32_16x16x32_bf16 v[18:21], v[152:155], v[142:145], v[18:21]
	ds_read_b64_tr_b16 v[152:153], v210 offset:43680
	ds_read_b64_tr_b16 v[154:155], v210 offset:48032
	s_waitcnt lgkmcnt(8)
	v_mfma_f32_16x16x32_bf16 v[22:25], v[156:159], v[126:129], v[22:25]
	v_mfma_f32_16x16x32_bf16 v[18:21], v[156:159], v[138:141], v[18:21]
	ds_read_b64_tr_b16 v[156:157], v210 offset:52384
	ds_read_b64_tr_b16 v[158:159], v210 offset:56736
	s_waitcnt lgkmcnt(8)
	v_mfma_f32_16x16x32_bf16 v[22:25], v[160:163], v[122:125], v[22:25]
	v_mfma_f32_16x16x32_bf16 v[18:21], v[160:163], v[134:137], v[18:21]
	ds_read_b64_tr_b16 v[160:161], v210 offset:61088
	ds_read_b64_tr_b16 v[162:163], v210 offset:65440
	s_waitcnt lgkmcnt(8)
	v_mfma_f32_16x16x32_bf16 v[22:25], v[164:167], v[114:117], v[22:25]
	v_mfma_f32_16x16x32_bf16 v[18:21], v[164:167], v[118:121], v[18:21]
	ds_read_b64_tr_b16 v[164:165], v210 offset:35008
	ds_read_b64_tr_b16 v[166:167], v210 offset:39360
	s_waitcnt lgkmcnt(8)
	v_mfma_f32_16x16x32_bf16 v[14:17], v[148:151], v[130:133], v[14:17]
	v_mfma_f32_16x16x32_bf16 v[10:13], v[148:151], v[142:145], v[10:13]
	ds_read_b64_tr_b16 v[148:149], v210 offset:43712
	ds_read_b64_tr_b16 v[150:151], v210 offset:48064
	s_waitcnt lgkmcnt(8)
	v_mfma_f32_16x16x32_bf16 v[14:17], v[152:155], v[126:129], v[14:17]
	v_mfma_f32_16x16x32_bf16 v[10:13], v[152:155], v[138:141], v[10:13]
	ds_read_b64_tr_b16 v[152:153], v210 offset:52416
	ds_read_b64_tr_b16 v[154:155], v210 offset:56768
	s_waitcnt lgkmcnt(8)
	v_mfma_f32_16x16x32_bf16 v[14:17], v[156:159], v[122:125], v[14:17]
	v_mfma_f32_16x16x32_bf16 v[10:13], v[156:159], v[134:137], v[10:13]
	ds_read_b64_tr_b16 v[156:157], v210 offset:61120
	ds_read_b64_tr_b16 v[158:159], v210 offset:65472
	s_waitcnt lgkmcnt(8)
	v_mfma_f32_16x16x32_bf16 v[14:17], v[160:163], v[114:117], v[14:17]
	v_mfma_f32_16x16x32_bf16 v[10:13], v[160:163], v[118:121], v[10:13]
	ds_read_b64_tr_b16 v[160:161], v210 offset:35040
	ds_read_b64_tr_b16 v[162:163], v210 offset:39392
	s_waitcnt lgkmcnt(8)
	v_mfma_f32_16x16x32_bf16 v[6:9], v[164:167], v[130:133], v[6:9]
	v_mfma_f32_16x16x32_bf16 v[2:5], v[164:167], v[142:145], v[2:5]
	ds_read_b64_tr_b16 v[164:165], v210 offset:43744
	ds_read_b64_tr_b16 v[166:167], v210 offset:48096
	s_waitcnt lgkmcnt(8)
	v_mfma_f32_16x16x32_bf16 v[6:9], v[148:151], v[126:129], v[6:9]
	v_mfma_f32_16x16x32_bf16 v[2:5], v[148:151], v[138:141], v[2:5]
	ds_read_b64_tr_b16 v[148:149], v210 offset:52448
	ds_read_b64_tr_b16 v[150:151], v210 offset:56800
	s_waitcnt lgkmcnt(8)
	v_mfma_f32_16x16x32_bf16 v[6:9], v[152:155], v[122:125], v[6:9]
	v_mfma_f32_16x16x32_bf16 v[2:5], v[152:155], v[134:137], v[2:5]
	ds_read_b64_tr_b16 v[152:153], v210 offset:61152
	ds_read_b64_tr_b16 v[154:155], v210 offset:65504
	s_waitcnt lgkmcnt(8)
	v_mfma_f32_16x16x32_bf16 v[6:9], v[156:159], v[114:117], v[6:9]
	v_mfma_f32_16x16x32_bf16 v[2:5], v[156:159], v[118:121], v[2:5]
	s_waitcnt lgkmcnt(6)
	v_mfma_f32_16x16x32_bf16 v[110:113], v[160:163], v[130:133], v[110:113]
	v_mfma_f32_16x16x32_bf16 v[106:109], v[160:163], v[142:145], v[106:109]
	s_waitcnt lgkmcnt(4)
	v_mfma_f32_16x16x32_bf16 v[110:113], v[164:167], v[126:129], v[110:113]
	v_mfma_f32_16x16x32_bf16 v[106:109], v[164:167], v[138:141], v[106:109]
	s_waitcnt lgkmcnt(2)
	v_mfma_f32_16x16x32_bf16 v[110:113], v[148:151], v[122:125], v[110:113]
	v_mfma_f32_16x16x32_bf16 v[106:109], v[148:151], v[134:137], v[106:109]
	s_waitcnt lgkmcnt(0)
	v_mfma_f32_16x16x32_bf16 v[110:113], v[152:155], v[114:117], v[110:113]
	v_mfma_f32_16x16x32_bf16 v[106:109], v[152:155], v[118:121], v[106:109]
	s_cbranch_scc0 .LBB0_239
	v_mov_b32_e32 v192, v214
	v_mov_b32_e32 v148, v213
	v_mov_b32_e32 v216, v146
	v_mov_b32_e32 v215, v147
	s_branch .LBB0_245
